# MLA latent epilogue: og stores paired through v_permlane32_swap into 8 dwordx4 per lane instead of 16 dwordx2 (row-per-lane store tail)
# speedup vs baseline: 1.0076x; 1.0076x over previous
.LBB0_502:
	s_or_b64 exec, exec, s[16:17]
	v_add_f32_e32 v64, v64, v65
	v_fmac_f32_e32 v64, v186, v96
	v_rcp_f32_e32 v67, v64
	s_lshl_b64 s[14:15], s[14:15], 12
	s_add_u32 s14, s23, s14
	s_addc_u32 s15, s24, s15
	v_mul_f32_e32 v16, v67, v16
	v_mul_f32_e32 v17, v67, v17
	v_cvt_pk_bf16_f32 v80, v16, v17
	v_mul_f32_e32 v16, v67, v18
	v_mul_f32_e32 v17, v67, v19
	v_cvt_pk_bf16_f32 v81, v16, v17
	v_mul_f32_e32 v16, v67, v20
	v_mul_f32_e32 v17, v67, v21
	v_cvt_pk_bf16_f32 v82, v16, v17
	v_mul_f32_e32 v16, v67, v22
	v_mul_f32_e32 v17, v67, v23
	v_cvt_pk_bf16_f32 v83, v16, v17
	v_mul_f32_e32 v16, v67, v24
	v_mul_f32_e32 v17, v67, v25
	v_cvt_pk_bf16_f32 v84, v16, v17
	v_mul_f32_e32 v16, v67, v26
	v_mul_f32_e32 v17, v67, v27
	v_cvt_pk_bf16_f32 v85, v16, v17
	v_mul_f32_e32 v16, v67, v28
	v_mul_f32_e32 v17, v67, v29
	v_cvt_pk_bf16_f32 v86, v16, v17
	v_mul_f32_e32 v16, v67, v30
	v_mul_f32_e32 v17, v67, v31
	v_cvt_pk_bf16_f32 v87, v16, v17
	v_mul_f32_e32 v16, v67, v32
	v_mul_f32_e32 v17, v67, v33
	v_cvt_pk_bf16_f32 v88, v16, v17
	v_mul_f32_e32 v16, v67, v34
	v_mul_f32_e32 v17, v67, v35
	v_cvt_pk_bf16_f32 v89, v16, v17
	v_mul_f32_e32 v16, v67, v36
	v_mul_f32_e32 v17, v67, v37
	v_cvt_pk_bf16_f32 v90, v16, v17
	v_mul_f32_e32 v16, v67, v38
	v_mul_f32_e32 v17, v67, v39
	v_cvt_pk_bf16_f32 v91, v16, v17
	v_mul_f32_e32 v16, v67, v40
	v_mul_f32_e32 v17, v67, v41
	v_cvt_pk_bf16_f32 v92, v16, v17
	v_mul_f32_e32 v16, v67, v42
	v_mul_f32_e32 v17, v67, v43
	v_cvt_pk_bf16_f32 v93, v16, v17
	v_mul_f32_e32 v16, v67, v44
	v_mul_f32_e32 v17, v67, v45
	v_cvt_pk_bf16_f32 v94, v16, v17
	v_mul_f32_e32 v16, v67, v46
	v_mul_f32_e32 v17, v67, v47
	v_cvt_pk_bf16_f32 v95, v16, v17
	v_mul_f32_e32 v16, v67, v48
	v_mul_f32_e32 v17, v67, v49
	v_cvt_pk_bf16_f32 v76, v16, v17
	v_mul_f32_e32 v16, v67, v50
	v_mul_f32_e32 v17, v67, v51
	v_cvt_pk_bf16_f32 v77, v16, v17
	v_mul_f32_e32 v16, v67, v52
	v_mul_f32_e32 v17, v67, v53
	v_cvt_pk_bf16_f32 v78, v16, v17
	v_mul_f32_e32 v16, v67, v54
	v_mul_f32_e32 v17, v67, v55
	v_cvt_pk_bf16_f32 v79, v16, v17
	v_mul_f32_e32 v16, v67, v56
	v_mul_f32_e32 v17, v67, v57
	v_cvt_pk_bf16_f32 v72, v16, v17
	v_mul_f32_e32 v16, v67, v58
	v_mul_f32_e32 v17, v67, v59
	v_cvt_pk_bf16_f32 v73, v16, v17
	v_mul_f32_e32 v16, v67, v60
	v_mul_f32_e32 v17, v67, v61
	v_mul_f32_e32 v0, v67, v0
	v_mul_f32_e32 v1, v67, v1
	v_cvt_pk_bf16_f32 v74, v16, v17
	v_mul_f32_e32 v16, v67, v62
	v_mul_f32_e32 v17, v67, v63
	v_cvt_pk_bf16_f32 v75, v16, v17
	v_cvt_pk_bf16_f32 v68, v0, v1
	v_mul_f32_e32 v0, v67, v2
	v_mul_f32_e32 v1, v67, v3
	v_cvt_pk_bf16_f32 v69, v0, v1
	v_mul_f32_e32 v0, v67, v4
	v_mul_f32_e32 v1, v67, v5
	v_cvt_pk_bf16_f32 v70, v0, v1
	v_mul_f32_e32 v0, v67, v6
	v_mul_f32_e32 v1, v67, v7
	s_lshl_b32 s16, s0, 8
	v_cvt_pk_bf16_f32 v71, v0, v1
	v_mul_f32_e32 v0, v67, v8
	v_mul_f32_e32 v1, v67, v9
	s_add_u32 s14, s14, s16
	v_cvt_pk_bf16_f32 v64, v0, v1
	v_mul_f32_e32 v0, v67, v10
	v_mul_f32_e32 v1, v67, v11
	s_addc_u32 s15, s15, 0
	v_cvt_pk_bf16_f32 v65, v0, v1
	v_mul_f32_e32 v0, v67, v12
	v_mul_f32_e32 v1, v67, v13
	s_lshl_b32 s0, s0, 15
	v_cvt_pk_bf16_f32 v66, v0, v1
	v_mul_f32_e32 v0, v67, v14
	v_mul_f32_e32 v1, v67, v15
	v_lshl_add_u64 v[62:63], v[152:153], 0, s[0:1]
	v_cvt_pk_bf16_f32 v67, v0, v1
	global_load_dwordx2 v[0:1], v[62:63], off
	global_load_dwordx2 v[2:3], v[62:63], off offset:16
	global_load_dwordx2 v[16:17], v[62:63], off offset:32
	global_load_dwordx2 v[18:19], v[62:63], off offset:48
	global_load_dwordx2 v[20:21], v[62:63], off offset:64
	global_load_dwordx2 v[22:23], v[62:63], off offset:80
	global_load_dwordx2 v[24:25], v[62:63], off offset:96
	global_load_dwordx2 v[26:27], v[62:63], off offset:112
	global_load_dwordx2 v[28:29], v[62:63], off offset:128
	global_load_dwordx2 v[30:31], v[62:63], off offset:144
	v_add_co_u32_e32 v48, vcc, s36, v62
	s_waitcnt vmcnt(0)
	v_mfma_f32_32x32x16_bf16 v[0:15], v[0:3], v[80:83], 0
	v_addc_co_u32_e32 v49, vcc, 0, v63, vcc
	v_add_co_u32_e32 v138, vcc, s37, v62
	s_add_i32 s41, s41, s60
	s_nop 0
	v_addc_co_u32_e32 v139, vcc, 0, v63, vcc
	v_mfma_f32_32x32x16_bf16 v[0:15], v[16:19], v[84:87], v[0:15]
	global_load_dwordx2 v[16:17], v[62:63], off offset:160
	global_load_dwordx2 v[18:19], v[62:63], off offset:176
	v_add_co_u32_e32 v146, vcc, s40, v62
	s_cmpk_gt_i32 s41, 0x7ff
	s_nop 0
	v_addc_co_u32_e32 v147, vcc, 0, v63, vcc
	v_mfma_f32_32x32x16_bf16 v[0:15], v[20:23], v[88:91], v[0:15]
	global_load_dwordx2 v[20:21], v[62:63], off offset:192
	global_load_dwordx2 v[22:23], v[62:63], off offset:208
	v_mfma_f32_32x32x16_bf16 v[0:15], v[24:27], v[92:95], v[0:15]
	global_load_dwordx2 v[24:25], v[48:49], off
	global_load_dwordx2 v[26:27], v[48:49], off offset:16
	global_load_dwordx2 v[32:33], v[62:63], off offset:224
	global_load_dwordx2 v[34:35], v[62:63], off offset:240
	global_load_dwordx2 v[36:37], v[48:49], off offset:32
	global_load_dwordx2 v[38:39], v[48:49], off offset:48
	global_load_dwordx2 v[40:41], v[48:49], off offset:64
	global_load_dwordx2 v[42:43], v[48:49], off offset:80
	global_load_dwordx2 v[44:45], v[48:49], off offset:96
	global_load_dwordx2 v[46:47], v[48:49], off offset:112
	v_lshl_add_u64 v[62:63], s[14:15], 0, v[154:155]
	v_lshl_add_u64 v[96:97], v[62:63], 0, v[150:151]
	v_lshlrev_b32_e32 v198, 3, v172
	v_mov_b32_e32 v199, 0
	v_lshl_add_u64 v[198:199], v[96:97], 0, v[198:199]
	v_mfma_f32_32x32x16_bf16 v[0:15], v[28:31], v[76:79], v[0:15]
	s_waitcnt vmcnt(0)
	v_mfma_f32_32x32x16_bf16 v[0:15], v[16:19], v[72:75], v[0:15]
	v_mfma_f32_32x32x16_bf16 v[0:15], v[20:23], v[68:71], v[0:15]
	v_mfma_f32_32x32x16_bf16 v[0:15], v[32:35], v[64:67], v[0:15]
	global_load_dwordx2 v[32:33], v[138:139], off
	global_load_dwordx2 v[34:35], v[138:139], off offset:16
	global_load_dwordx2 v[50:51], v[138:139], off offset:32
	global_load_dwordx2 v[52:53], v[138:139], off offset:48
	global_load_dwordx2 v[54:55], v[138:139], off offset:64
	global_load_dwordx2 v[56:57], v[138:139], off offset:80
	global_load_dwordx2 v[58:59], v[138:139], off offset:96
	global_load_dwordx2 v[60:61], v[138:139], off offset:112
	global_load_dwordx2 v[98:99], v[146:147], off
	global_load_dwordx2 v[100:101], v[146:147], off offset:16
	global_load_dwordx2 v[102:103], v[146:147], off offset:32
	global_load_dwordx2 v[104:105], v[146:147], off offset:48
	global_load_dwordx2 v[106:107], v[146:147], off offset:64
	global_load_dwordx2 v[108:109], v[146:147], off offset:80
	global_load_dwordx2 v[158:159], v[96:97], off
	v_mfma_f32_32x32x16_bf16 v[16:31], v[24:27], v[80:83], 0
	global_load_dwordx2 v[110:111], v[146:147], off offset:96
	global_load_dwordx2 v[112:113], v[146:147], off offset:112
	global_load_dwordx2 v[114:115], v[48:49], off offset:128
	global_load_dwordx2 v[116:117], v[48:49], off offset:144
	global_load_dwordx2 v[118:119], v[48:49], off offset:160
	global_load_dwordx2 v[120:121], v[48:49], off offset:176
	global_load_dwordx2 v[122:123], v[48:49], off offset:192
	global_load_dwordx2 v[124:125], v[48:49], off offset:208
	global_load_dwordx2 v[126:127], v[48:49], off offset:224
	global_load_dwordx2 v[128:129], v[48:49], off offset:240
	global_load_dwordx2 v[130:131], v[138:139], off offset:128
	global_load_dwordx2 v[132:133], v[138:139], off offset:144
	global_load_dwordx2 v[134:135], v[138:139], off offset:160
	global_load_dwordx2 v[136:137], v[138:139], off offset:176
	v_mfma_f32_32x32x16_bf16 v[16:31], v[36:39], v[84:87], v[16:31]
	v_mfma_f32_32x32x16_bf16 v[16:31], v[40:43], v[88:91], v[16:31]
	v_mfma_f32_32x32x16_bf16 v[16:31], v[44:47], v[92:95], v[16:31]
	s_waitcnt vmcnt(0)
	v_mfma_f32_32x32x16_bf16 v[32:47], v[32:35], v[80:83], 0
	v_mfma_f32_32x32x16_bf16 v[32:47], v[50:53], v[84:87], v[32:47]
	v_mfma_f32_32x32x16_bf16 v[32:47], v[54:57], v[88:91], v[32:47]
	v_mfma_f32_32x32x16_bf16 v[32:47], v[58:61], v[92:95], v[32:47]
	v_mfma_f32_32x32x16_bf16 v[48:63], v[98:101], v[80:83], 0
	global_load_dwordx2 v[80:81], v[138:139], off offset:192
	global_load_dwordx2 v[82:83], v[138:139], off offset:208
	global_load_dwordx2 v[98:99], v[138:139], off offset:224
	global_load_dwordx2 v[100:101], v[138:139], off offset:240
	s_nop 0
	global_load_dwordx2 v[138:139], v[146:147], off offset:128
	global_load_dwordx2 v[140:141], v[146:147], off offset:144
	global_load_dwordx2 v[142:143], v[146:147], off offset:160
	global_load_dwordx2 v[144:145], v[146:147], off offset:176
	v_mfma_f32_32x32x16_bf16 v[48:63], v[102:105], v[84:87], v[48:63]
	global_load_dwordx2 v[84:85], v[146:147], off offset:192
	global_load_dwordx2 v[86:87], v[146:147], off offset:208
	global_load_dwordx2 v[102:103], v[146:147], off offset:224
	global_load_dwordx2 v[104:105], v[146:147], off offset:240
	v_lshlrev_b32_e32 v146, 16, v158
	v_and_b32_e32 v147, 0xffff0000, v158
	v_lshlrev_b32_e32 v158, 16, v159
	v_mul_f32_e32 v0, v0, v146
	v_mul_f32_e32 v1, v1, v147
	v_cvt_pk_bf16_f32 v0, v0, v1
	v_mfma_f32_32x32x16_bf16 v[48:63], v[106:109], v[88:91], v[48:63]
	v_and_b32_e32 v88, 0xffff0000, v159
	v_mul_f32_e32 v1, v2, v158
	v_mul_f32_e32 v2, v3, v88
	v_cvt_pk_bf16_f32 v1, v1, v2
	s_nop 0
	v_mov_b32_e32 v200, v0
	v_mov_b32_e32 v201, v1
	v_mfma_f32_32x32x16_bf16 v[16:31], v[114:117], v[76:79], v[16:31]
	s_waitcnt vmcnt(0)
	v_lshlrev_b32_e32 v0, 16, v208
	v_and_b32_e32 v1, 0xffff0000, v208
	v_lshlrev_b32_e32 v2, 16, v209
	v_and_b32_e32 v3, 0xffff0000, v209
	v_mul_f32_e32 v0, v4, v0
	v_mul_f32_e32 v1, v5, v1
	v_mul_f32_e32 v2, v6, v2
	v_mul_f32_e32 v3, v7, v3
	v_cvt_pk_bf16_f32 v0, v0, v1
	v_cvt_pk_bf16_f32 v1, v2, v3
	v_mfma_f32_32x32x16_bf16 v[16:31], v[118:121], v[72:75], v[16:31]
	v_mov_b32_e32 v202, v0
	v_mov_b32_e32 v203, v1
	s_nop 1
	v_permlane32_swap_b32_e32 v200, v202
	v_permlane32_swap_b32_e32 v201, v203
	global_store_dwordx4 v[198:199], v[200:203], off
	v_lshlrev_b32_e32 v0, 16, v210
	v_and_b32_e32 v1, 0xffff0000, v210
	v_lshlrev_b32_e32 v2, 16, v211
	v_and_b32_e32 v3, 0xffff0000, v211
	v_mul_f32_e32 v0, v8, v0
	v_mul_f32_e32 v1, v9, v1
	v_mul_f32_e32 v2, v10, v2
	v_mul_f32_e32 v3, v11, v3
	v_cvt_pk_bf16_f32 v0, v0, v1
	v_cvt_pk_bf16_f32 v1, v2, v3
	v_mfma_f32_32x32x16_bf16 v[16:31], v[122:125], v[68:71], v[16:31]
	v_mov_b32_e32 v200, v0
	v_mov_b32_e32 v201, v1
	v_lshlrev_b32_e32 v0, 16, v212
	v_and_b32_e32 v1, 0xffff0000, v212
	v_lshlrev_b32_e32 v2, 16, v213
	v_and_b32_e32 v3, 0xffff0000, v213
	v_mul_f32_e32 v0, v12, v0
	v_mul_f32_e32 v1, v13, v1
	v_mul_f32_e32 v2, v14, v2
	v_mul_f32_e32 v3, v15, v3
	v_cvt_pk_bf16_f32 v0, v0, v1
	v_cvt_pk_bf16_f32 v1, v2, v3
	v_mfma_f32_32x32x16_bf16 v[16:31], v[126:129], v[64:67], v[16:31]
	v_mov_b32_e32 v202, v0
	v_mov_b32_e32 v203, v1
	s_nop 1
	v_permlane32_swap_b32_e32 v200, v202
	v_permlane32_swap_b32_e32 v201, v203
	global_store_dwordx4 v[198:199], v[200:203], off offset:32
	v_lshlrev_b32_e32 v0, 16, v214
	v_and_b32_e32 v1, 0xffff0000, v214
	v_lshlrev_b32_e32 v2, 16, v215
	v_and_b32_e32 v3, 0xffff0000, v215
	s_nop 5
	v_mul_f32_e32 v0, v16, v0
	v_mul_f32_e32 v1, v17, v1
	v_mul_f32_e32 v2, v18, v2
	v_mul_f32_e32 v3, v19, v3
	v_cvt_pk_bf16_f32 v0, v0, v1
	v_cvt_pk_bf16_f32 v1, v2, v3
	v_mfma_f32_32x32x16_bf16 v[32:47], v[130:133], v[76:79], v[32:47]
	v_mov_b32_e32 v200, v0
	v_mov_b32_e32 v201, v1
	v_lshlrev_b32_e32 v0, 16, v216
	v_and_b32_e32 v1, 0xffff0000, v216
	v_lshlrev_b32_e32 v2, 16, v217
	v_and_b32_e32 v3, 0xffff0000, v217
	v_mul_f32_e32 v0, v20, v0
	v_mul_f32_e32 v1, v21, v1
	v_mul_f32_e32 v2, v22, v2
	v_mul_f32_e32 v3, v23, v3
	v_cvt_pk_bf16_f32 v0, v0, v1
	v_cvt_pk_bf16_f32 v1, v2, v3
	v_mfma_f32_32x32x16_bf16 v[32:47], v[134:137], v[72:75], v[32:47]
	v_mov_b32_e32 v202, v0
	v_mov_b32_e32 v203, v1
	s_nop 1
	v_permlane32_swap_b32_e32 v200, v202
	v_permlane32_swap_b32_e32 v201, v203
	global_store_dwordx4 v[198:199], v[200:203], off offset:64
	v_lshlrev_b32_e32 v0, 16, v218
	v_and_b32_e32 v1, 0xffff0000, v218
	v_lshlrev_b32_e32 v2, 16, v219
	v_and_b32_e32 v3, 0xffff0000, v219
	v_mul_f32_e32 v0, v24, v0
	v_mul_f32_e32 v1, v25, v1
	v_mul_f32_e32 v2, v26, v2
	v_mul_f32_e32 v3, v27, v3
	v_cvt_pk_bf16_f32 v0, v0, v1
	v_cvt_pk_bf16_f32 v1, v2, v3
	v_mfma_f32_32x32x16_bf16 v[32:47], v[80:83], v[68:71], v[32:47]
	v_mov_b32_e32 v200, v0
	v_mov_b32_e32 v201, v1
	v_lshlrev_b32_e32 v0, 16, v220
	v_and_b32_e32 v1, 0xffff0000, v220
	v_lshlrev_b32_e32 v2, 16, v221
	v_and_b32_e32 v3, 0xffff0000, v221
	v_mul_f32_e32 v0, v28, v0
	v_mul_f32_e32 v1, v29, v1
	v_mul_f32_e32 v2, v30, v2
	v_mul_f32_e32 v3, v31, v3
	v_cvt_pk_bf16_f32 v0, v0, v1
	v_cvt_pk_bf16_f32 v1, v2, v3
	v_mfma_f32_32x32x16_bf16 v[32:47], v[98:101], v[64:67], v[32:47]
	v_mov_b32_e32 v202, v0
	v_mov_b32_e32 v203, v1
	s_nop 1
	v_permlane32_swap_b32_e32 v200, v202
	v_permlane32_swap_b32_e32 v201, v203
	global_store_dwordx4 v[198:199], v[200:203], off offset:96
	v_lshlrev_b32_e32 v0, 16, v222
	v_and_b32_e32 v1, 0xffff0000, v222
	v_lshlrev_b32_e32 v2, 16, v223
	v_and_b32_e32 v3, 0xffff0000, v223
	s_nop 5
	v_mul_f32_e32 v0, v32, v0
	v_mul_f32_e32 v1, v33, v1
	v_mul_f32_e32 v2, v34, v2
	v_mul_f32_e32 v3, v35, v3
	v_cvt_pk_bf16_f32 v0, v0, v1
	v_cvt_pk_bf16_f32 v1, v2, v3
	v_mfma_f32_32x32x16_bf16 v[48:63], v[110:113], v[92:95], v[48:63]
	v_mov_b32_e32 v200, v0
	v_mov_b32_e32 v201, v1
	v_lshlrev_b32_e32 v0, 16, v224
	v_and_b32_e32 v1, 0xffff0000, v224
	v_lshlrev_b32_e32 v2, 16, v225
	v_and_b32_e32 v3, 0xffff0000, v225
	v_mul_f32_e32 v0, v36, v0
	v_mul_f32_e32 v1, v37, v1
	v_mul_f32_e32 v2, v38, v2
	v_mul_f32_e32 v3, v39, v3
	v_cvt_pk_bf16_f32 v0, v0, v1
	v_cvt_pk_bf16_f32 v1, v2, v3
	v_mfma_f32_32x32x16_bf16 v[48:63], v[138:141], v[76:79], v[48:63]
	v_mov_b32_e32 v202, v0
	v_mov_b32_e32 v203, v1
	s_nop 1
	v_permlane32_swap_b32_e32 v200, v202
	v_permlane32_swap_b32_e32 v201, v203
	global_store_dwordx4 v[198:199], v[200:203], off offset:128
	v_lshlrev_b32_e32 v0, 16, v226
	v_and_b32_e32 v1, 0xffff0000, v226
	v_lshlrev_b32_e32 v2, 16, v227
	v_and_b32_e32 v3, 0xffff0000, v227
	v_mul_f32_e32 v0, v40, v0
	v_mul_f32_e32 v1, v41, v1
	v_mul_f32_e32 v2, v42, v2
	v_mul_f32_e32 v3, v43, v3
	v_cvt_pk_bf16_f32 v0, v0, v1
	v_cvt_pk_bf16_f32 v1, v2, v3
	v_mfma_f32_32x32x16_bf16 v[48:63], v[142:145], v[72:75], v[48:63]
	v_mov_b32_e32 v200, v0
	v_mov_b32_e32 v201, v1
	v_lshlrev_b32_e32 v0, 16, v228
	v_and_b32_e32 v1, 0xffff0000, v228
	v_lshlrev_b32_e32 v2, 16, v229
	v_and_b32_e32 v3, 0xffff0000, v229
	v_mul_f32_e32 v0, v44, v0
	v_mul_f32_e32 v1, v45, v1
	v_mul_f32_e32 v2, v46, v2
	v_mul_f32_e32 v3, v47, v3
	v_cvt_pk_bf16_f32 v0, v0, v1
	v_cvt_pk_bf16_f32 v1, v2, v3
	v_mfma_f32_32x32x16_bf16 v[48:63], v[84:87], v[68:71], v[48:63]
	v_mov_b32_e32 v202, v0
	v_mov_b32_e32 v203, v1
	s_nop 1
	v_permlane32_swap_b32_e32 v200, v202
	v_permlane32_swap_b32_e32 v201, v203
	global_store_dwordx4 v[198:199], v[200:203], off offset:160
	v_lshlrev_b32_e32 v0, 16, v230
	v_mfma_f32_32x32x16_bf16 v[48:63], v[102:105], v[64:67], v[48:63]
	v_and_b32_e32 v1, 0xffff0000, v230
	v_lshlrev_b32_e32 v2, 16, v231
	v_and_b32_e32 v3, 0xffff0000, v231
	s_nop 8
	v_mul_f32_e32 v0, v48, v0
	v_mul_f32_e32 v1, v49, v1
	v_mul_f32_e32 v2, v50, v2
	v_mul_f32_e32 v3, v51, v3
	v_cvt_pk_bf16_f32 v0, v0, v1
	v_cvt_pk_bf16_f32 v1, v2, v3
	s_nop 0
	v_mov_b32_e32 v200, v0
	v_mov_b32_e32 v201, v1
	v_lshlrev_b32_e32 v0, 16, v232
	v_and_b32_e32 v1, 0xffff0000, v232
	v_lshlrev_b32_e32 v2, 16, v233
	v_and_b32_e32 v3, 0xffff0000, v233
	v_mul_f32_e32 v0, v52, v0
	v_mul_f32_e32 v1, v53, v1
	v_mul_f32_e32 v2, v54, v2
	v_mul_f32_e32 v3, v55, v3
	v_cvt_pk_bf16_f32 v0, v0, v1
	v_cvt_pk_bf16_f32 v1, v2, v3
	s_nop 0
	v_mov_b32_e32 v202, v0
	v_mov_b32_e32 v203, v1
	s_nop 1
	v_permlane32_swap_b32_e32 v200, v202
	v_permlane32_swap_b32_e32 v201, v203
	global_store_dwordx4 v[198:199], v[200:203], off offset:192
	v_lshlrev_b32_e32 v0, 16, v234
	v_and_b32_e32 v1, 0xffff0000, v234
	v_lshlrev_b32_e32 v2, 16, v235
	v_and_b32_e32 v3, 0xffff0000, v235
	v_mul_f32_e32 v0, v56, v0
	v_mul_f32_e32 v1, v57, v1
	v_mul_f32_e32 v2, v58, v2
	v_mul_f32_e32 v3, v59, v3
	v_cvt_pk_bf16_f32 v0, v0, v1
	v_cvt_pk_bf16_f32 v1, v2, v3
	s_nop 0
	v_mov_b32_e32 v200, v0
	v_mov_b32_e32 v201, v1
	v_lshlrev_b32_e32 v0, 16, v236
	v_and_b32_e32 v1, 0xffff0000, v236
	v_lshlrev_b32_e32 v2, 16, v237
	v_and_b32_e32 v3, 0xffff0000, v237
	v_mul_f32_e32 v0, v60, v0
	v_mul_f32_e32 v1, v61, v1
	v_mul_f32_e32 v2, v62, v2
	v_mul_f32_e32 v3, v63, v3
	v_cvt_pk_bf16_f32 v0, v0, v1
	v_cvt_pk_bf16_f32 v1, v2, v3
	v_mov_b32_e32 v202, v0
	v_mov_b32_e32 v203, v1
	s_nop 1
	v_permlane32_swap_b32_e32 v200, v202
	v_permlane32_swap_b32_e32 v201, v203
	global_store_dwordx4 v[198:199], v[200:203], off offset:224
	s_waitcnt lgkmcnt(0)
	s_barrier
	s_cbranch_scc1 .LBB0_525
